# expert-dot loop regenerated: three-operand dot2 starting from 0 (no zero movs), DPP-operand adds for the 8-lane reduction interleaved into the next pair, early row reload
# speedup vs baseline: 1.0081x; 1.0081x over previous
; template <int CTRL> DI float dpp_add(float x) { return x + __uint_as_float(__builtin_amdgcn_update_dpp(0u, __float_as_uint(x), CTRL, 0xf, 0xf, true)); }
; DI void eseg_load(ESeg& r, __amdgpu_buffer_rsrc_t rs, int voff) { r.a = __builtin_amdgcn_raw_buffer_load_b128(rs, voff, 0, 0); r.b = __builtin_amdgcn_raw_buffer_load_b64(rs, voff + 16, 0, 0); }
; DI int id_of(const u32x4 (&d)[2], int r, unsigned mask = 0xffffu) { const unsigned w = d[r >> 3][(r >> 1) & 3]; return (r & 1) ? (int)((w >> 16) & mask) : (int)(w & mask); }
;     ...
;         const int tn = t + nwx, tnn = tn + nwx, tn_c = tn < nrows ? tn : t, tnn_c = tnn < nrows ? tnn : t;
;         ids_load(idnn, RI16, tnn_c, g);
;         u32x2 hq[8];
; #pragma unroll
;         for (int c = 0; c < 8; ++c) hq[c] = hp[c];
;         __builtin_amdgcn_sched_barrier(0);
; #pragma unroll
;         for (int c = 0; c < 8; ++c) hp[c] = *(const u32x2*)(Hs + (size_t)tn_c * D + c * 256);
;         __builtin_amdgcn_sched_barrier(0);
;         float o0 = 0.f, o1 = 0.f;
; #pragma unroll
;         for (int r = 0; r < 16; ++r) {
;             if (MODE == 2) { o0 += __uint_as_float(rw[r].a.x ^ rw[r].a.w ^ rw[r].b.y); eseg_load(rw[r], US, id_of(idn, r, mask) * ESEG + s24); if (r & 1) __builtin_amdgcn_sched_barrier(0); continue; }
;             typedef __bf16 bfx2 __attribute__((ext_vector_type(2))); typedef __bf16 bfx32 __attribute__((ext_vector_type(32)));
;             const bfx32 rr = __builtin_amdgcn_cvt_scalef32_pk32_bf16_fp6((v6i){(int)rw[r].a.x, (int)rw[r].a.y, (int)rw[r].a.z, (int)rw[r].a.w, (int)rw[r].b.x, (int)rw[r].b.y}, 1.0f);
;             float dA = 0.f, dB = 0.f;
;     ...
;             DOT2(0, dA); DOT2(1, dB); DOT2(2, dA); DOT2(3, dB); DOT2(4, dA); DOT2(5, dB); DOT2(6, dA); DOT2(7, dB); DOT2(8, dA); DOT2(9, dB); DOT2(10, dA); DOT2(11, dB); DOT2(12, dA); DOT2(13, dB); DOT2(14, dA); DOT2(15, dB);
;     ...
;             float d = dA + dB;
;             d = dpp_add<0xB1>(d); d = dpp_add<0x4E>(d); d = dpp_add<0x141>(d);
;             if ((r >> 1) == s) { if (r & 1) o1 = d; else o0 = d; }
;             if (MODE != 1) eseg_load(rw[r], US, id_of(idn, r, mask) * ESEG + s24);
;             else asm volatile("" : "+v"(rw[r].a.x), "+v"(rw[r].a.y), "+v"(rw[r].a.z), "+v"(rw[r].a.w), "+v"(rw[r].b.x), "+v"(rw[r].b.y));
;             if (r & 1) __builtin_amdgcn_sched_barrier(0);
.LBB0_979:
	s_add_i32 s11, s10, s4
	s_add_i32 s8, s5, s10
	s_cmp_lt_i32 s8, s15
	s_cselect_b32 s8, s8, s10
	s_ashr_i32 s9, s8, 31
	s_lshl_b64 s[8:9], s[8:9], 8
	v_lshl_add_u64 v[0:1], v[132:133], 0, s[8:9]
	global_load_dwordx4 v[112:115], v[0:1], off offset:16
	global_load_dwordx4 v[116:119], v[0:1], off
	s_cmp_lt_i32 s11, s15
	s_cselect_b64 s[8:9], -1, 0
	s_and_b64 s[12:13], s[8:9], exec
	s_cselect_b32 s12, s11, s10
	s_ashr_i32 s13, s12, 31
	s_lshl_b64 s[12:13], s[12:13], 12
	v_lshl_add_u64 v[0:1], v[130:131], 0, s[12:13]
	global_load_dwordx2 v[136:137], v[0:1], off
	global_load_dwordx2 v[138:139], v[0:1], off offset:512
	global_load_dwordx2 v[140:141], v[0:1], off offset:1024
	global_load_dwordx2 v[142:143], v[0:1], off offset:1536
	global_load_dwordx2 v[144:145], v[0:1], off offset:2048
	global_load_dwordx2 v[146:147], v[0:1], off offset:2560
	global_load_dwordx2 v[148:149], v[0:1], off offset:3072
	global_load_dwordx2 v[150:151], v[0:1], off offset:3584
	s_waitcnt vmcnt(41)
	v_cvt_scalef32_pk32_bf16_fp6 v[0:15], v[16:21], 1.0
	v_and_b32_e32 v195, 0xffff, v124
	v_mad_u32_u24 v195, v195, s14, v194
	buffer_load_dwordx4 v[16:19], v195, s[48:51], 0 offen
	buffer_load_dwordx2 v[20:21], v195, s[48:51], 0 offen offset:16
	v_dot2_f32_bf16 v168, v0, v158, 0
	v_dot2_f32_bf16 v170, v1, v159, 0
	v_dot2_f32_bf16 v168, v2, v156, v168
	v_dot2_f32_bf16 v170, v3, v157, v170
	v_dot2_f32_bf16 v168, v4, v154, v168
	v_dot2_f32_bf16 v170, v5, v155, v170
	v_dot2_f32_bf16 v168, v6, v152, v168
	v_dot2_f32_bf16 v170, v7, v153, v170
	v_dot2_f32_bf16 v168, v8, v166, v168
	v_dot2_f32_bf16 v170, v9, v167, v170
	v_dot2_f32_bf16 v168, v10, v164, v168
	v_dot2_f32_bf16 v170, v11, v165, v170
	v_dot2_f32_bf16 v168, v12, v162, v168
	v_dot2_f32_bf16 v170, v13, v163, v170
	v_dot2_f32_bf16 v168, v14, v160, v168
	v_dot2_f32_bf16 v170, v15, v161, v170
	s_waitcnt vmcnt(41)
	v_cvt_scalef32_pk32_bf16_fp6 v[0:15], v[94:99], 1.0
	v_lshrrev_b32_e32 v195, 16, v124
	v_mad_u32_u24 v195, v195, s14, v194
	buffer_load_dwordx4 v[94:97], v195, s[48:51], 0 offen
	buffer_load_dwordx2 v[98:99], v195, s[48:51], 0 offen offset:16
	v_dot2_f32_bf16 v169, v0, v158, 0
	v_dot2_f32_bf16 v171, v1, v159, 0
	v_dot2_f32_bf16 v169, v2, v156, v169
	v_dot2_f32_bf16 v171, v3, v157, v171
	v_dot2_f32_bf16 v169, v4, v154, v169
	v_dot2_f32_bf16 v171, v5, v155, v171
	v_dot2_f32_bf16 v169, v6, v152, v169
	v_dot2_f32_bf16 v171, v7, v153, v171
	v_dot2_f32_bf16 v169, v8, v166, v169
	v_dot2_f32_bf16 v171, v9, v167, v171
	v_dot2_f32_bf16 v169, v10, v164, v169
	v_dot2_f32_bf16 v171, v11, v165, v171
	v_dot2_f32_bf16 v169, v12, v162, v169
	v_dot2_f32_bf16 v171, v13, v163, v171
	v_dot2_f32_bf16 v169, v14, v160, v169
	v_dot2_f32_bf16 v171, v15, v161, v171
	s_waitcnt vmcnt(41)
	v_cvt_scalef32_pk32_bf16_fp6 v[0:15], v[22:27], 1.0
	v_and_b32_e32 v195, 0xffff, v125
	v_mad_u32_u24 v195, v195, s14, v194
	buffer_load_dwordx4 v[22:25], v195, s[48:51], 0 offen
	buffer_load_dwordx2 v[26:27], v195, s[48:51], 0 offen offset:16
	v_dot2_f32_bf16 v172, v0, v158, 0
	v_dot2_f32_bf16 v174, v1, v159, 0
	v_dot2_f32_bf16 v172, v2, v156, v172
	v_dot2_f32_bf16 v174, v3, v157, v174
	v_pk_add_f32 v[170:171], v[168:169], v[170:171]
	v_dot2_f32_bf16 v172, v4, v154, v172
	v_dot2_f32_bf16 v174, v5, v155, v174
	v_add_f32_dpp v170, v170, v170 quad_perm:[1,0,3,2] row_mask:0xf bank_mask:0xf bound_ctrl:1
	v_add_f32_dpp v171, v171, v171 quad_perm:[1,0,3,2] row_mask:0xf bank_mask:0xf bound_ctrl:1
	v_dot2_f32_bf16 v172, v6, v152, v172
	v_dot2_f32_bf16 v174, v7, v153, v174
	v_add_f32_dpp v170, v170, v170 quad_perm:[2,3,0,1] row_mask:0xf bank_mask:0xf bound_ctrl:1
	v_add_f32_dpp v171, v171, v171 quad_perm:[2,3,0,1] row_mask:0xf bank_mask:0xf bound_ctrl:1
	v_dot2_f32_bf16 v172, v8, v166, v172
	v_dot2_f32_bf16 v174, v9, v167, v174
	v_add_f32_dpp v170, v170, v170 row_half_mirror row_mask:0xf bank_mask:0xf bound_ctrl:1
	v_add_f32_dpp v171, v171, v171 row_half_mirror row_mask:0xf bank_mask:0xf bound_ctrl:1
	v_dot2_f32_bf16 v172, v10, v164, v172
	v_dot2_f32_bf16 v174, v11, v165, v174
	v_cndmask_b32_e64 v196, 0, v170, s[36:37]
	v_cndmask_b32_e64 v197, 0, v171, s[36:37]
	v_dot2_f32_bf16 v172, v12, v162, v172
	v_dot2_f32_bf16 v174, v13, v163, v174
	v_dot2_f32_bf16 v172, v14, v160, v172
	v_dot2_f32_bf16 v174, v15, v161, v174
	s_waitcnt vmcnt(41)
	v_cvt_scalef32_pk32_bf16_fp6 v[0:15], v[46:51], 1.0
	v_lshrrev_b32_e32 v195, 16, v125
	v_mad_u32_u24 v195, v195, s14, v194
	buffer_load_dwordx4 v[46:49], v195, s[48:51], 0 offen
	buffer_load_dwordx2 v[50:51], v195, s[48:51], 0 offen offset:16
	v_dot2_f32_bf16 v173, v0, v158, 0
	v_dot2_f32_bf16 v175, v1, v159, 0
	v_dot2_f32_bf16 v173, v2, v156, v173
	v_dot2_f32_bf16 v175, v3, v157, v175
	v_dot2_f32_bf16 v173, v4, v154, v173
	v_dot2_f32_bf16 v175, v5, v155, v175
	v_dot2_f32_bf16 v173, v6, v152, v173
	v_dot2_f32_bf16 v175, v7, v153, v175
	v_dot2_f32_bf16 v173, v8, v166, v173
	v_dot2_f32_bf16 v175, v9, v167, v175
	v_dot2_f32_bf16 v173, v10, v164, v173
	v_dot2_f32_bf16 v175, v11, v165, v175
	v_dot2_f32_bf16 v173, v12, v162, v173
	v_dot2_f32_bf16 v175, v13, v163, v175
	v_dot2_f32_bf16 v173, v14, v160, v173
	v_dot2_f32_bf16 v175, v15, v161, v175
	s_waitcnt vmcnt(41)
; template <int CTRL> DI float dpp_add(float x) { return x + __uint_as_float(__builtin_amdgcn_update_dpp(0u, __float_as_uint(x), CTRL, 0xf, 0xf, true)); }
; DI void eseg_load(ESeg& r, __amdgpu_buffer_rsrc_t rs, int voff) { r.a = __builtin_amdgcn_raw_buffer_load_b128(rs, voff, 0, 0); r.b = __builtin_amdgcn_raw_buffer_load_b64(rs, voff + 16, 0, 0); }
; DI int id_of(const u32x4 (&d)[2], int r, unsigned mask = 0xffffu) { const unsigned w = d[r >> 3][(r >> 1) & 3]; return (r & 1) ? (int)((w >> 16) & mask) : (int)(w & mask); }
; #define DOT2(k, acc) acc = __builtin_amdgcn_fdot2_f32_bf16(__builtin_shufflevector(rr, rr, 2 * (k), 2 * (k) + 1), __builtin_bit_cast(bfx2, ((k) & 1) ? hq[(k) >> 1].y : hq[(k) >> 1].x), acc, false)
;     ...
;         for (int r = 0; r < 16; ++r) {
;             if (MODE == 2) { o0 += __uint_as_float(rw[r].a.x ^ rw[r].a.w ^ rw[r].b.y); eseg_load(rw[r], US, id_of(idn, r, mask) * ESEG + s24); if (r & 1) __builtin_amdgcn_sched_barrier(0); continue; }
;             typedef __bf16 bfx2 __attribute__((ext_vector_type(2))); typedef __bf16 bfx32 __attribute__((ext_vector_type(32)));
;             const bfx32 rr = __builtin_amdgcn_cvt_scalef32_pk32_bf16_fp6((v6i){(int)rw[r].a.x, (int)rw[r].a.y, (int)rw[r].a.z, (int)rw[r].a.w, (int)rw[r].b.x, (int)rw[r].b.y}, 1.0f);
;             float dA = 0.f, dB = 0.f;
;     ...
;             DOT2(0, dA); DOT2(1, dB); DOT2(2, dA); DOT2(3, dB); DOT2(4, dA); DOT2(5, dB); DOT2(6, dA); DOT2(7, dB); DOT2(8, dA); DOT2(9, dB); DOT2(10, dA); DOT2(11, dB); DOT2(12, dA); DOT2(13, dB); DOT2(14, dA); DOT2(15, dB);
;     ...
;             float d = dA + dB;
;             d = dpp_add<0xB1>(d); d = dpp_add<0x4E>(d); d = dpp_add<0x141>(d);
;             if ((r >> 1) == s) { if (r & 1) o1 = d; else o0 = d; }
;             if (MODE != 1) eseg_load(rw[r], US, id_of(idn, r, mask) * ESEG + s24);
;             else asm volatile("" : "+v"(rw[r].a.x), "+v"(rw[r].a.y), "+v"(rw[r].a.z), "+v"(rw[r].a.w), "+v"(rw[r].b.x), "+v"(rw[r].b.y));
;             if (r & 1) __builtin_amdgcn_sched_barrier(0);
	v_cvt_scalef32_pk32_bf16_fp6 v[0:15], v[28:33], 1.0
	v_and_b32_e32 v195, 0xffff, v126
	v_mad_u32_u24 v195, v195, s14, v194
	buffer_load_dwordx4 v[28:31], v195, s[48:51], 0 offen
	buffer_load_dwordx2 v[32:33], v195, s[48:51], 0 offen offset:16
	v_dot2_f32_bf16 v124, v0, v158, 0
	v_dot2_f32_bf16 v176, v1, v159, 0
	v_dot2_f32_bf16 v124, v2, v156, v124
	v_dot2_f32_bf16 v176, v3, v157, v176
	v_pk_add_f32 v[174:175], v[172:173], v[174:175]
	v_dot2_f32_bf16 v124, v4, v154, v124
	v_dot2_f32_bf16 v176, v5, v155, v176
	v_add_f32_dpp v174, v174, v174 quad_perm:[1,0,3,2] row_mask:0xf bank_mask:0xf bound_ctrl:1
	v_add_f32_dpp v175, v175, v175 quad_perm:[1,0,3,2] row_mask:0xf bank_mask:0xf bound_ctrl:1
	v_dot2_f32_bf16 v124, v6, v152, v124
	v_dot2_f32_bf16 v176, v7, v153, v176
	v_add_f32_dpp v174, v174, v174 quad_perm:[2,3,0,1] row_mask:0xf bank_mask:0xf bound_ctrl:1
	v_add_f32_dpp v175, v175, v175 quad_perm:[2,3,0,1] row_mask:0xf bank_mask:0xf bound_ctrl:1
	v_dot2_f32_bf16 v124, v8, v166, v124
	v_dot2_f32_bf16 v176, v9, v167, v176
	v_add_f32_dpp v174, v174, v174 row_half_mirror row_mask:0xf bank_mask:0xf bound_ctrl:1
	v_add_f32_dpp v175, v175, v175 row_half_mirror row_mask:0xf bank_mask:0xf bound_ctrl:1
	v_dot2_f32_bf16 v124, v10, v164, v124
	v_dot2_f32_bf16 v176, v11, v165, v176
	v_cndmask_b32_e64 v196, v196, v174, s[38:39]
	v_cndmask_b32_e64 v197, v197, v175, s[38:39]
	v_dot2_f32_bf16 v124, v12, v162, v124
	v_dot2_f32_bf16 v176, v13, v163, v176
	v_dot2_f32_bf16 v124, v14, v160, v124
	v_dot2_f32_bf16 v176, v15, v161, v176
	s_waitcnt vmcnt(41)
	v_cvt_scalef32_pk32_bf16_fp6 v[0:15], v[64:69], 1.0
	v_lshrrev_b32_e32 v195, 16, v126
	v_mad_u32_u24 v195, v195, s14, v194
	buffer_load_dwordx4 v[64:67], v195, s[48:51], 0 offen
	buffer_load_dwordx2 v[68:69], v195, s[48:51], 0 offen offset:16
	v_dot2_f32_bf16 v125, v0, v158, 0
	v_dot2_f32_bf16 v177, v1, v159, 0
	v_dot2_f32_bf16 v125, v2, v156, v125
	v_dot2_f32_bf16 v177, v3, v157, v177
	v_dot2_f32_bf16 v125, v4, v154, v125
	v_dot2_f32_bf16 v177, v5, v155, v177
	v_dot2_f32_bf16 v125, v6, v152, v125
	v_dot2_f32_bf16 v177, v7, v153, v177
	v_dot2_f32_bf16 v125, v8, v166, v125
	v_dot2_f32_bf16 v177, v9, v167, v177
	v_dot2_f32_bf16 v125, v10, v164, v125
	v_dot2_f32_bf16 v177, v11, v165, v177
	v_dot2_f32_bf16 v125, v12, v162, v125
	v_dot2_f32_bf16 v177, v13, v163, v177
	v_dot2_f32_bf16 v125, v14, v160, v125
	v_dot2_f32_bf16 v177, v15, v161, v177
	s_waitcnt vmcnt(41)
	v_cvt_scalef32_pk32_bf16_fp6 v[0:15], v[34:39], 1.0
	v_and_b32_e32 v195, 0xffff, v127
	v_mad_u32_u24 v195, v195, s14, v194
	buffer_load_dwordx4 v[34:37], v195, s[48:51], 0 offen
	buffer_load_dwordx2 v[38:39], v195, s[48:51], 0 offen offset:16
	v_dot2_f32_bf16 v178, v0, v158, 0
	v_dot2_f32_bf16 v180, v1, v159, 0
	v_dot2_f32_bf16 v178, v2, v156, v178
	v_dot2_f32_bf16 v180, v3, v157, v180
	v_pk_add_f32 v[176:177], v[124:125], v[176:177]
	v_dot2_f32_bf16 v178, v4, v154, v178
	v_dot2_f32_bf16 v180, v5, v155, v180
	v_add_f32_dpp v176, v176, v176 quad_perm:[1,0,3,2] row_mask:0xf bank_mask:0xf bound_ctrl:1
	v_add_f32_dpp v177, v177, v177 quad_perm:[1,0,3,2] row_mask:0xf bank_mask:0xf bound_ctrl:1
	v_dot2_f32_bf16 v178, v6, v152, v178
	v_dot2_f32_bf16 v180, v7, v153, v180
	v_add_f32_dpp v176, v176, v176 quad_perm:[2,3,0,1] row_mask:0xf bank_mask:0xf bound_ctrl:1
	v_add_f32_dpp v177, v177, v177 quad_perm:[2,3,0,1] row_mask:0xf bank_mask:0xf bound_ctrl:1
	v_dot2_f32_bf16 v178, v8, v166, v178
	v_dot2_f32_bf16 v180, v9, v167, v180
	v_add_f32_dpp v176, v176, v176 row_half_mirror row_mask:0xf bank_mask:0xf bound_ctrl:1
	v_add_f32_dpp v177, v177, v177 row_half_mirror row_mask:0xf bank_mask:0xf bound_ctrl:1
	v_dot2_f32_bf16 v178, v10, v164, v178
	v_dot2_f32_bf16 v180, v11, v165, v180
	v_cndmask_b32_e64 v196, v196, v176, s[40:41]
	v_cndmask_b32_e64 v197, v197, v177, s[40:41]
	v_dot2_f32_bf16 v178, v12, v162, v178
	v_dot2_f32_bf16 v180, v13, v163, v180
	v_dot2_f32_bf16 v178, v14, v160, v178
	v_dot2_f32_bf16 v180, v15, v161, v180
	s_waitcnt vmcnt(41)
	v_cvt_scalef32_pk32_bf16_fp6 v[0:15], v[76:81], 1.0
	v_lshrrev_b32_e32 v195, 16, v127
	v_mad_u32_u24 v195, v195, s14, v194
	buffer_load_dwordx4 v[76:79], v195, s[48:51], 0 offen
	buffer_load_dwordx2 v[80:81], v195, s[48:51], 0 offen offset:16
	v_dot2_f32_bf16 v179, v0, v158, 0
	v_dot2_f32_bf16 v181, v1, v159, 0
	v_dot2_f32_bf16 v179, v2, v156, v179
	v_dot2_f32_bf16 v181, v3, v157, v181
	v_dot2_f32_bf16 v179, v4, v154, v179
	v_dot2_f32_bf16 v181, v5, v155, v181
	v_dot2_f32_bf16 v179, v6, v152, v179
	v_dot2_f32_bf16 v181, v7, v153, v181
	v_dot2_f32_bf16 v179, v8, v166, v179
	v_dot2_f32_bf16 v181, v9, v167, v181
	v_dot2_f32_bf16 v179, v10, v164, v179
	v_dot2_f32_bf16 v181, v11, v165, v181
	v_dot2_f32_bf16 v179, v12, v162, v179
	v_dot2_f32_bf16 v181, v13, v163, v181
	v_dot2_f32_bf16 v179, v14, v160, v179
	v_dot2_f32_bf16 v181, v15, v161, v181
	s_waitcnt vmcnt(41)
; template <int CTRL> DI float dpp_add(float x) { return x + __uint_as_float(__builtin_amdgcn_update_dpp(0u, __float_as_uint(x), CTRL, 0xf, 0xf, true)); }
; DI void eseg_load(ESeg& r, __amdgpu_buffer_rsrc_t rs, int voff) { r.a = __builtin_amdgcn_raw_buffer_load_b128(rs, voff, 0, 0); r.b = __builtin_amdgcn_raw_buffer_load_b64(rs, voff + 16, 0, 0); }
; DI int id_of(const u32x4 (&d)[2], int r, unsigned mask = 0xffffu) { const unsigned w = d[r >> 3][(r >> 1) & 3]; return (r & 1) ? (int)((w >> 16) & mask) : (int)(w & mask); }
; #define DOT2(k, acc) acc = __builtin_amdgcn_fdot2_f32_bf16(__builtin_shufflevector(rr, rr, 2 * (k), 2 * (k) + 1), __builtin_bit_cast(bfx2, ((k) & 1) ? hq[(k) >> 1].y : hq[(k) >> 1].x), acc, false)
;     ...
;         for (int r = 0; r < 16; ++r) {
;             if (MODE == 2) { o0 += __uint_as_float(rw[r].a.x ^ rw[r].a.w ^ rw[r].b.y); eseg_load(rw[r], US, id_of(idn, r, mask) * ESEG + s24); if (r & 1) __builtin_amdgcn_sched_barrier(0); continue; }
;             typedef __bf16 bfx2 __attribute__((ext_vector_type(2))); typedef __bf16 bfx32 __attribute__((ext_vector_type(32)));
;             const bfx32 rr = __builtin_amdgcn_cvt_scalef32_pk32_bf16_fp6((v6i){(int)rw[r].a.x, (int)rw[r].a.y, (int)rw[r].a.z, (int)rw[r].a.w, (int)rw[r].b.x, (int)rw[r].b.y}, 1.0f);
;             float dA = 0.f, dB = 0.f;
;     ...
;             DOT2(0, dA); DOT2(1, dB); DOT2(2, dA); DOT2(3, dB); DOT2(4, dA); DOT2(5, dB); DOT2(6, dA); DOT2(7, dB); DOT2(8, dA); DOT2(9, dB); DOT2(10, dA); DOT2(11, dB); DOT2(12, dA); DOT2(13, dB); DOT2(14, dA); DOT2(15, dB);
;     ...
;             float d = dA + dB;
;             d = dpp_add<0xB1>(d); d = dpp_add<0x4E>(d); d = dpp_add<0x141>(d);
;             if ((r >> 1) == s) { if (r & 1) o1 = d; else o0 = d; }
;             if (MODE != 1) eseg_load(rw[r], US, id_of(idn, r, mask) * ESEG + s24);
;             else asm volatile("" : "+v"(rw[r].a.x), "+v"(rw[r].a.y), "+v"(rw[r].a.z), "+v"(rw[r].a.w), "+v"(rw[r].b.x), "+v"(rw[r].b.y));
;             if (r & 1) __builtin_amdgcn_sched_barrier(0);
	v_cvt_scalef32_pk32_bf16_fp6 v[0:15], v[40:45], 1.0
	v_and_b32_e32 v195, 0xffff, v120
	v_mad_u32_u24 v195, v195, s14, v194
	buffer_load_dwordx4 v[40:43], v195, s[48:51], 0 offen
	buffer_load_dwordx2 v[44:45], v195, s[48:51], 0 offen offset:16
	v_dot2_f32_bf16 v126, v0, v158, 0
	v_dot2_f32_bf16 v182, v1, v159, 0
	v_dot2_f32_bf16 v126, v2, v156, v126
	v_dot2_f32_bf16 v182, v3, v157, v182
	v_pk_add_f32 v[180:181], v[178:179], v[180:181]
	v_dot2_f32_bf16 v126, v4, v154, v126
	v_dot2_f32_bf16 v182, v5, v155, v182
	v_add_f32_dpp v180, v180, v180 quad_perm:[1,0,3,2] row_mask:0xf bank_mask:0xf bound_ctrl:1
	v_add_f32_dpp v181, v181, v181 quad_perm:[1,0,3,2] row_mask:0xf bank_mask:0xf bound_ctrl:1
	v_dot2_f32_bf16 v126, v6, v152, v126
	v_dot2_f32_bf16 v182, v7, v153, v182
	v_add_f32_dpp v180, v180, v180 quad_perm:[2,3,0,1] row_mask:0xf bank_mask:0xf bound_ctrl:1
	v_add_f32_dpp v181, v181, v181 quad_perm:[2,3,0,1] row_mask:0xf bank_mask:0xf bound_ctrl:1
	v_dot2_f32_bf16 v126, v8, v166, v126
	v_dot2_f32_bf16 v182, v9, v167, v182
	v_add_f32_dpp v180, v180, v180 row_half_mirror row_mask:0xf bank_mask:0xf bound_ctrl:1
	v_add_f32_dpp v181, v181, v181 row_half_mirror row_mask:0xf bank_mask:0xf bound_ctrl:1
	v_dot2_f32_bf16 v126, v10, v164, v126
	v_dot2_f32_bf16 v182, v11, v165, v182
	v_cndmask_b32_e64 v196, v196, v180, s[42:43]
	v_cndmask_b32_e64 v197, v197, v181, s[42:43]
	v_dot2_f32_bf16 v126, v12, v162, v126
	v_dot2_f32_bf16 v182, v13, v163, v182
	v_dot2_f32_bf16 v126, v14, v160, v126
	v_dot2_f32_bf16 v182, v15, v161, v182
	s_waitcnt vmcnt(41)
	v_cvt_scalef32_pk32_bf16_fp6 v[0:15], v[82:87], 1.0
	v_lshrrev_b32_e32 v195, 16, v120
	v_mad_u32_u24 v195, v195, s14, v194
	buffer_load_dwordx4 v[82:85], v195, s[48:51], 0 offen
	buffer_load_dwordx2 v[86:87], v195, s[48:51], 0 offen offset:16
	v_dot2_f32_bf16 v127, v0, v158, 0
	v_dot2_f32_bf16 v183, v1, v159, 0
	v_dot2_f32_bf16 v127, v2, v156, v127
	v_dot2_f32_bf16 v183, v3, v157, v183
	v_dot2_f32_bf16 v127, v4, v154, v127
	v_dot2_f32_bf16 v183, v5, v155, v183
	v_dot2_f32_bf16 v127, v6, v152, v127
	v_dot2_f32_bf16 v183, v7, v153, v183
	v_dot2_f32_bf16 v127, v8, v166, v127
	v_dot2_f32_bf16 v183, v9, v167, v183
	v_dot2_f32_bf16 v127, v10, v164, v127
	v_dot2_f32_bf16 v183, v11, v165, v183
	v_dot2_f32_bf16 v127, v12, v162, v127
	v_dot2_f32_bf16 v183, v13, v163, v183
	v_dot2_f32_bf16 v127, v14, v160, v127
	v_dot2_f32_bf16 v183, v15, v161, v183
	s_waitcnt vmcnt(41)
	v_cvt_scalef32_pk32_bf16_fp6 v[0:15], v[58:63], 1.0
	v_and_b32_e32 v195, 0xffff, v121
	v_mad_u32_u24 v195, v195, s14, v194
	buffer_load_dwordx4 v[58:61], v195, s[48:51], 0 offen
	buffer_load_dwordx2 v[62:63], v195, s[48:51], 0 offen offset:16
	v_dot2_f32_bf16 v184, v0, v158, 0
	v_dot2_f32_bf16 v186, v1, v159, 0
	v_dot2_f32_bf16 v184, v2, v156, v184
	v_dot2_f32_bf16 v186, v3, v157, v186
	v_pk_add_f32 v[182:183], v[126:127], v[182:183]
	v_dot2_f32_bf16 v184, v4, v154, v184
	v_dot2_f32_bf16 v186, v5, v155, v186
	v_add_f32_dpp v182, v182, v182 quad_perm:[1,0,3,2] row_mask:0xf bank_mask:0xf bound_ctrl:1
	v_add_f32_dpp v183, v183, v183 quad_perm:[1,0,3,2] row_mask:0xf bank_mask:0xf bound_ctrl:1
	v_dot2_f32_bf16 v184, v6, v152, v184
	v_dot2_f32_bf16 v186, v7, v153, v186
	v_add_f32_dpp v182, v182, v182 quad_perm:[2,3,0,1] row_mask:0xf bank_mask:0xf bound_ctrl:1
	v_add_f32_dpp v183, v183, v183 quad_perm:[2,3,0,1] row_mask:0xf bank_mask:0xf bound_ctrl:1
	v_dot2_f32_bf16 v184, v8, v166, v184
	v_dot2_f32_bf16 v186, v9, v167, v186
	v_add_f32_dpp v182, v182, v182 row_half_mirror row_mask:0xf bank_mask:0xf bound_ctrl:1
	v_add_f32_dpp v183, v183, v183 row_half_mirror row_mask:0xf bank_mask:0xf bound_ctrl:1
	v_dot2_f32_bf16 v184, v10, v164, v184
	v_dot2_f32_bf16 v186, v11, v165, v186
	v_cndmask_b32_e64 v196, v196, v182, s[44:45]
	v_cndmask_b32_e64 v197, v197, v183, s[44:45]
	v_dot2_f32_bf16 v184, v12, v162, v184
	v_dot2_f32_bf16 v186, v13, v163, v186
	v_dot2_f32_bf16 v184, v14, v160, v184
	v_dot2_f32_bf16 v186, v15, v161, v186
	s_waitcnt vmcnt(41)
	v_cvt_scalef32_pk32_bf16_fp6 v[0:15], v[88:93], 1.0
	v_lshrrev_b32_e32 v195, 16, v121
	v_mad_u32_u24 v195, v195, s14, v194
	buffer_load_dwordx4 v[88:91], v195, s[48:51], 0 offen
	buffer_load_dwordx2 v[92:93], v195, s[48:51], 0 offen offset:16
	v_dot2_f32_bf16 v185, v0, v158, 0
	v_dot2_f32_bf16 v187, v1, v159, 0
	v_dot2_f32_bf16 v185, v2, v156, v185
	v_dot2_f32_bf16 v187, v3, v157, v187
	v_dot2_f32_bf16 v185, v4, v154, v185
	v_dot2_f32_bf16 v187, v5, v155, v187
	v_dot2_f32_bf16 v185, v6, v152, v185
	v_dot2_f32_bf16 v187, v7, v153, v187
	v_dot2_f32_bf16 v185, v8, v166, v185
	v_dot2_f32_bf16 v187, v9, v167, v187
	v_dot2_f32_bf16 v185, v10, v164, v185
	v_dot2_f32_bf16 v187, v11, v165, v187
	v_dot2_f32_bf16 v185, v12, v162, v185
	v_dot2_f32_bf16 v187, v13, v163, v187
	v_dot2_f32_bf16 v185, v14, v160, v185
	v_dot2_f32_bf16 v187, v15, v161, v187
	s_waitcnt vmcnt(41)
; template <int CTRL> DI float dpp_add(float x) { return x + __uint_as_float(__builtin_amdgcn_update_dpp(0u, __float_as_uint(x), CTRL, 0xf, 0xf, true)); }
; DI void eseg_load(ESeg& r, __amdgpu_buffer_rsrc_t rs, int voff) { r.a = __builtin_amdgcn_raw_buffer_load_b128(rs, voff, 0, 0); r.b = __builtin_amdgcn_raw_buffer_load_b64(rs, voff + 16, 0, 0); }
; DI int id_of(const u32x4 (&d)[2], int r, unsigned mask = 0xffffu) { const unsigned w = d[r >> 3][(r >> 1) & 3]; return (r & 1) ? (int)((w >> 16) & mask) : (int)(w & mask); }
; #define DOT2(k, acc) acc = __builtin_amdgcn_fdot2_f32_bf16(__builtin_shufflevector(rr, rr, 2 * (k), 2 * (k) + 1), __builtin_bit_cast(bfx2, ((k) & 1) ? hq[(k) >> 1].y : hq[(k) >> 1].x), acc, false)
;     ...
;         for (int r = 0; r < 16; ++r) {
;             if (MODE == 2) { o0 += __uint_as_float(rw[r].a.x ^ rw[r].a.w ^ rw[r].b.y); eseg_load(rw[r], US, id_of(idn, r, mask) * ESEG + s24); if (r & 1) __builtin_amdgcn_sched_barrier(0); continue; }
;             typedef __bf16 bfx2 __attribute__((ext_vector_type(2))); typedef __bf16 bfx32 __attribute__((ext_vector_type(32)));
;             const bfx32 rr = __builtin_amdgcn_cvt_scalef32_pk32_bf16_fp6((v6i){(int)rw[r].a.x, (int)rw[r].a.y, (int)rw[r].a.z, (int)rw[r].a.w, (int)rw[r].b.x, (int)rw[r].b.y}, 1.0f);
;             float dA = 0.f, dB = 0.f;
;     ...
;             DOT2(0, dA); DOT2(1, dB); DOT2(2, dA); DOT2(3, dB); DOT2(4, dA); DOT2(5, dB); DOT2(6, dA); DOT2(7, dB); DOT2(8, dA); DOT2(9, dB); DOT2(10, dA); DOT2(11, dB); DOT2(12, dA); DOT2(13, dB); DOT2(14, dA); DOT2(15, dB);
;     ...
;             float d = dA + dB;
;             d = dpp_add<0xB1>(d); d = dpp_add<0x4E>(d); d = dpp_add<0x141>(d);
;             if ((r >> 1) == s) { if (r & 1) o1 = d; else o0 = d; }
;             if (MODE != 1) eseg_load(rw[r], US, id_of(idn, r, mask) * ESEG + s24);
;             else asm volatile("" : "+v"(rw[r].a.x), "+v"(rw[r].a.y), "+v"(rw[r].a.z), "+v"(rw[r].a.w), "+v"(rw[r].b.x), "+v"(rw[r].b.y));
;             if (r & 1) __builtin_amdgcn_sched_barrier(0);
;         }
;         *(f32x2*)(P + (size_t)t * 128 + g * 16 + 2 * s) = (f32x2){o0, o1};
;         if (tn >= nrows) break;
;         t = tn; idn[0] = idnn[0]; idn[1] = idnn[1];
	v_cvt_scalef32_pk32_bf16_fp6 v[0:15], v[70:75], 1.0
	v_and_b32_e32 v195, 0xffff, v122
	v_mad_u32_u24 v195, v195, s14, v194
	buffer_load_dwordx4 v[70:73], v195, s[48:51], 0 offen
	buffer_load_dwordx2 v[74:75], v195, s[48:51], 0 offen offset:16
	v_dot2_f32_bf16 v120, v0, v158, 0
	v_dot2_f32_bf16 v188, v1, v159, 0
	v_dot2_f32_bf16 v120, v2, v156, v120
	v_dot2_f32_bf16 v188, v3, v157, v188
	v_pk_add_f32 v[186:187], v[184:185], v[186:187]
	v_dot2_f32_bf16 v120, v4, v154, v120
	v_dot2_f32_bf16 v188, v5, v155, v188
	v_add_f32_dpp v186, v186, v186 quad_perm:[1,0,3,2] row_mask:0xf bank_mask:0xf bound_ctrl:1
	v_add_f32_dpp v187, v187, v187 quad_perm:[1,0,3,2] row_mask:0xf bank_mask:0xf bound_ctrl:1
	v_dot2_f32_bf16 v120, v6, v152, v120
	v_dot2_f32_bf16 v188, v7, v153, v188
	v_add_f32_dpp v186, v186, v186 quad_perm:[2,3,0,1] row_mask:0xf bank_mask:0xf bound_ctrl:1
	v_add_f32_dpp v187, v187, v187 quad_perm:[2,3,0,1] row_mask:0xf bank_mask:0xf bound_ctrl:1
	v_dot2_f32_bf16 v120, v8, v166, v120
	v_dot2_f32_bf16 v188, v9, v167, v188
	v_add_f32_dpp v186, v186, v186 row_half_mirror row_mask:0xf bank_mask:0xf bound_ctrl:1
	v_add_f32_dpp v187, v187, v187 row_half_mirror row_mask:0xf bank_mask:0xf bound_ctrl:1
	v_dot2_f32_bf16 v120, v10, v164, v120
	v_dot2_f32_bf16 v188, v11, v165, v188
	v_cndmask_b32_e64 v196, v196, v186, s[46:47]
	v_cndmask_b32_e64 v197, v197, v187, s[46:47]
	v_dot2_f32_bf16 v120, v12, v162, v120
	v_dot2_f32_bf16 v188, v13, v163, v188
	v_dot2_f32_bf16 v120, v14, v160, v120
	v_dot2_f32_bf16 v188, v15, v161, v188
	s_waitcnt vmcnt(41)
	v_cvt_scalef32_pk32_bf16_fp6 v[0:15], v[100:105], 1.0
	v_lshrrev_b32_e32 v195, 16, v122
	v_mad_u32_u24 v195, v195, s14, v194
	buffer_load_dwordx4 v[100:103], v195, s[48:51], 0 offen
	buffer_load_dwordx2 v[104:105], v195, s[48:51], 0 offen offset:16
	v_dot2_f32_bf16 v121, v0, v158, 0
	v_dot2_f32_bf16 v189, v1, v159, 0
	v_dot2_f32_bf16 v121, v2, v156, v121
	v_dot2_f32_bf16 v189, v3, v157, v189
	v_dot2_f32_bf16 v121, v4, v154, v121
	v_dot2_f32_bf16 v189, v5, v155, v189
	v_dot2_f32_bf16 v121, v6, v152, v121
	v_dot2_f32_bf16 v189, v7, v153, v189
	v_dot2_f32_bf16 v121, v8, v166, v121
	v_dot2_f32_bf16 v189, v9, v167, v189
	v_dot2_f32_bf16 v121, v10, v164, v121
	v_dot2_f32_bf16 v189, v11, v165, v189
	v_dot2_f32_bf16 v121, v12, v162, v121
	v_dot2_f32_bf16 v189, v13, v163, v189
	v_dot2_f32_bf16 v121, v14, v160, v121
	v_dot2_f32_bf16 v189, v15, v161, v189
	s_waitcnt vmcnt(41)
	v_cvt_scalef32_pk32_bf16_fp6 v[0:15], v[52:57], 1.0
	v_and_b32_e32 v195, 0xffff, v123
	v_mad_u32_u24 v195, v195, s14, v194
	buffer_load_dwordx4 v[52:55], v195, s[48:51], 0 offen
	buffer_load_dwordx2 v[56:57], v195, s[48:51], 0 offen offset:16
	v_dot2_f32_bf16 v190, v0, v158, 0
	v_dot2_f32_bf16 v192, v1, v159, 0
	v_dot2_f32_bf16 v190, v2, v156, v190
	v_dot2_f32_bf16 v192, v3, v157, v192
	v_pk_add_f32 v[188:189], v[120:121], v[188:189]
	v_dot2_f32_bf16 v190, v4, v154, v190
	v_dot2_f32_bf16 v192, v5, v155, v192
	v_add_f32_dpp v188, v188, v188 quad_perm:[1,0,3,2] row_mask:0xf bank_mask:0xf bound_ctrl:1
	v_add_f32_dpp v189, v189, v189 quad_perm:[1,0,3,2] row_mask:0xf bank_mask:0xf bound_ctrl:1
	v_dot2_f32_bf16 v190, v6, v152, v190
	v_dot2_f32_bf16 v192, v7, v153, v192
	v_add_f32_dpp v188, v188, v188 quad_perm:[2,3,0,1] row_mask:0xf bank_mask:0xf bound_ctrl:1
	v_add_f32_dpp v189, v189, v189 quad_perm:[2,3,0,1] row_mask:0xf bank_mask:0xf bound_ctrl:1
	v_dot2_f32_bf16 v190, v8, v166, v190
	v_dot2_f32_bf16 v192, v9, v167, v192
	v_add_f32_dpp v188, v188, v188 row_half_mirror row_mask:0xf bank_mask:0xf bound_ctrl:1
	v_add_f32_dpp v189, v189, v189 row_half_mirror row_mask:0xf bank_mask:0xf bound_ctrl:1
	v_dot2_f32_bf16 v190, v10, v164, v190
	v_dot2_f32_bf16 v192, v11, v165, v192
	v_cndmask_b32_e64 v196, v196, v188, s[0:1]
	v_cndmask_b32_e64 v197, v197, v189, s[0:1]
	v_dot2_f32_bf16 v190, v12, v162, v190
	v_dot2_f32_bf16 v192, v13, v163, v192
	v_dot2_f32_bf16 v190, v14, v160, v190
	v_dot2_f32_bf16 v192, v15, v161, v192
	s_waitcnt vmcnt(41)
	v_cvt_scalef32_pk32_bf16_fp6 v[0:15], v[106:111], 1.0
	v_lshrrev_b32_e32 v195, 16, v123
	v_mad_u32_u24 v195, v195, s14, v194
	buffer_load_dwordx4 v[106:109], v195, s[48:51], 0 offen
	buffer_load_dwordx2 v[110:111], v195, s[48:51], 0 offen offset:16
	v_dot2_f32_bf16 v191, v0, v158, 0
	v_dot2_f32_bf16 v193, v1, v159, 0
	v_dot2_f32_bf16 v191, v2, v156, v191
	v_dot2_f32_bf16 v193, v3, v157, v193
	v_dot2_f32_bf16 v191, v4, v154, v191
	v_dot2_f32_bf16 v193, v5, v155, v193
	v_dot2_f32_bf16 v191, v6, v152, v191
	v_dot2_f32_bf16 v193, v7, v153, v193
	v_dot2_f32_bf16 v191, v8, v166, v191
	v_dot2_f32_bf16 v193, v9, v167, v193
	v_dot2_f32_bf16 v191, v10, v164, v191
	v_dot2_f32_bf16 v193, v11, v165, v193
	v_dot2_f32_bf16 v191, v12, v162, v191
	v_dot2_f32_bf16 v193, v13, v163, v193
	v_dot2_f32_bf16 v191, v14, v160, v191
	v_dot2_f32_bf16 v193, v15, v161, v193
	s_waitcnt vmcnt(32)
	v_mov_b64_e32 v[122:123], v[114:115]
	v_mov_b64_e32 v[126:127], v[118:119]
	v_mov_b64_e32 v[120:121], v[112:113]
	v_mov_b64_e32 v[124:125], v[116:117]
	v_pk_add_f32 v[192:193], v[190:191], v[192:193]
	v_mov_b64_e32 v[160:161], v[150:151]
	v_mov_b64_e32 v[162:163], v[148:149]
	v_add_f32_dpp v192, v192, v192 quad_perm:[1,0,3,2] row_mask:0xf bank_mask:0xf bound_ctrl:1
	v_add_f32_dpp v193, v193, v193 quad_perm:[1,0,3,2] row_mask:0xf bank_mask:0xf bound_ctrl:1
	v_mov_b64_e32 v[164:165], v[146:147]
	v_mov_b64_e32 v[166:167], v[144:145]
	v_add_f32_dpp v192, v192, v192 quad_perm:[2,3,0,1] row_mask:0xf bank_mask:0xf bound_ctrl:1
	v_add_f32_dpp v193, v193, v193 quad_perm:[2,3,0,1] row_mask:0xf bank_mask:0xf bound_ctrl:1
	v_mov_b64_e32 v[152:153], v[142:143]
	v_mov_b64_e32 v[154:155], v[140:141]
	v_add_f32_dpp v192, v192, v192 row_half_mirror row_mask:0xf bank_mask:0xf bound_ctrl:1
	v_add_f32_dpp v193, v193, v193 row_half_mirror row_mask:0xf bank_mask:0xf bound_ctrl:1
	v_mov_b64_e32 v[156:157], v[138:139]
	v_mov_b64_e32 v[158:159], v[136:137]
	v_cndmask_b32_e64 v196, v196, v192, s[2:3]
	v_cndmask_b32_e64 v197, v197, v193, s[2:3]
	global_store_dwordx2 v[134:135], v[196:197], off
	v_lshl_add_u64 v[134:135], v[134:135], 0, s[6:7]
	s_and_b64 vcc, s[8:9], exec
	s_mov_b32 s10, s11
	s_cbranch_vccnz .LBB0_979
